# write-through publish + retention V-load widening + SIMD-balanced retention roles + attention K-tile prefetch
# speedup vs baseline: 1.0059x; 1.0056x over previous
;     DEVINL bf16_t* BVT() const { return (bf16_t*)(ws + OFF_BVT); }
;     DEVINL bf16_t* BKT() const { return (bf16_t*)(ws + OFF_BKT); }
;     DEVINL bf16_t* Y() const { return (bf16_t*)(ws + OFF_Y); }
; #define TID (opq_v((int)threadIdx.x))
; DEVINL float fexp2(float x) { return __builtin_amdgcn_exp2f(x); }
; DEVINL float flog2(float x) { return __builtin_amdgcn_logf(x); }
; DEVINL void ret_block(const Ctx& c, int b, int hd, unsigned char* lds) {
;     ...
;     const int tid = TID, lane = tid & 63, w = tid >> 6, r = lane & 31, h = lane >> 5;
;     const int qs = w & 3, dh = w >> 2, dvt = w >> 1, dt = w & 1;
;     const float lg2 = flog2(1.f - fexp2(-5.f - (float)hd));
;     const float gam = fexp2(lg2), gam128 = fexp2(lg2 * 128.f);
;     f32x16 sacc;
; #pragma unroll
;     for (int i = 0; i < 16; ++i) sacc[i] = 0.f;
;     const bf16_t* vtb = c.BVT() + (size_t)(b * 512 + hd * 128) * L;
;     const bf16_t* ktb = c.BKT() + (size_t)(b * 256 + hd * 64) * L;
;     bf16_t* Y = c.Y() + (size_t)T * 512;
;     ...
;             for (int d = 0; d < 2; ++d) {
;                 const bf16_t* vp = vtb + (size_t)(dh * 64 + d * 32 + r) * L + p0 + kt * 32 + 4 * h;
; #pragma unroll
;                 for (int s = 0; s < 2; ++s) {
;                     const u32x2 lo = *(const u32x2*)(vp + 16 * s), hi = *(const u32x2*)(vp + 16 * s + 8);
;                     u32x4 vv = {lo[0], lo[1], hi[0], hi[1]};
.LBB0_266:
	s_and_b64 vcc, exec, s[0:1]
	s_cbranch_vccz .LBB0_275
	s_and_b32 s12, s95, 3
	s_waitcnt vmcnt(0)
	v_cvt_f32_ubyte0_e32 v0, s12
	v_sub_f32_e32 v0, 0xc0a00000, v0
	v_exp_f32_e32 v0, v0
	v_mov_b32_e32 v2, v160
	s_sub_i32 s0, s95, 64
	v_sub_f32_e32 v0, 1.0, v0
	v_log_f32_e32 v93, v0
	v_ashrrev_i32_e32 v0, 6, v2
	v_and_b32_e32 v6, 1, v0
	v_lshlrev_b32_e32 v0, 5, v0
	v_and_b32_e32 v3, 31, v2
	v_and_b32_e32 v10, 0x60, v0
	v_bfe_u32 v231, v0, 7, 1
	v_mul_u32_u24_e32 v231, 0x60, v231
	v_xor_b32_e32 v10, v10, v231
	v_mul_f32_e32 v1, 0x43000000, v93
	v_or_b32_e32 v92, v10, v3
	v_exp_f32_e32 v88, v1
	v_lshlrev_b32_e32 v1, 6, v6
	v_lshlrev_b32_e32 v9, 1, v3
	v_cvt_f32_ubyte0_e32 v0, v92
	v_add3_u32 v9, 0, v1, v9
	v_mul_f32_e32 v0, v93, v0
	v_and_b32_e32 v1, 64, v162
	s_lshr_b32 s13, s0, 2
	v_ashrrev_i32_e32 v5, 8, v2
	s_lshl_b32 s14, s12, 7
	v_exp_f32_e32 v98, v0
	v_xor_b32_e32 v0, 32, v162
	v_add_u32_e32 v1, 64, v1
	s_lshl_b32 s4, s12, 8
	v_readlane_b32 s5, v247, 53
	v_bfe_u32 v4, v2, 5, 1
	v_ashrrev_i32_e32 v7, 2, v2
	v_lshlrev_b32_e32 v94, 6, v5
	v_cmp_lt_i32_e32 vcc, v0, v1
	s_add_u32 s4, s5, s4
	v_readlane_b32 s5, v247, 54
	v_and_b32_e32 v8, 0xffffffe0, v7
	v_lshlrev_b32_e32 v90, 2, v4
	v_cndmask_b32_e32 v0, v162, v0, vcc
	v_ashrrev_i32_e32 v95, 31, v94
	s_addc_u32 s5, s5, 0
	v_lshlrev_b32_e32 v64, 3, v4
	v_or_b32_e32 v11, v94, v3
	v_lshlrev_b32_e32 v96, 4, v4
	v_lshlrev_b32_e32 v122, 2, v0
	v_cmp_eq_u32_e64 s[0:1], 0, v4
	v_lshl_add_u64 v[0:1], v[94:95], 1, s[4:5]
	v_lshl_or_b32 v4, v6, 5, v3
	v_or_b32_e32 v6, v90, v8
	s_movk_i32 s4, 0x90
	v_mul_lo_u32 v6, v6, s4
	v_mul_lo_u32 v8, v11, s4
	s_add_u32 s4, s26, s14
	s_addc_u32 s5, s27, 0
	v_mov_b32_e32 v97, v65
	s_movk_i32 s15, 0x1100
	v_lshl_add_u64 v[104:105], s[4:5], 0, v[96:97]
	v_lshl_add_u64 v[106:107], v[0:1], 0, v[64:65]
	v_mad_i64_i32 v[0:1], s[4:5], v11, s15, 0
	s_mul_i32 s4, s13, 0x110000
	s_mul_i32 s5, s12, 0x44000
	s_add_i32 s66, s4, s5
	s_lshl_b64 s[4:5], s[66:67], 1
	v_readlane_b32 s8, v246, 26
	s_add_u32 s8, s8, s4
	v_readlane_b32 s9, v246, 29
	v_or_b32_e32 v0, v0, v64
	s_addc_u32 s9, s9, s5
	v_lshl_add_u64 v[108:109], s[8:9], 0, v[0:1]
	v_or_b32_e32 v0, 32, v11
	v_mad_i64_i32 v[0:1], s[10:11], v0, s15, 0
	v_or_b32_e32 v0, v0, v64
	v_lshl_add_u64 v[110:111], s[8:9], 0, v[0:1]
	s_movk_i32 s8, 0xffe0
	v_bfi_b32 v2, s8, v7, v2
	v_readlane_b32 s8, v246, 27
	v_readlane_b32 s9, v246, 28
	s_add_u32 s4, s8, s4
	s_addc_u32 s5, s9, s5
	v_mov_b64_e32 v[0:1], s[4:5]
	v_mad_i64_i32 v[112:113], s[4:5], v2, s15, v[0:1]
	s_mul_i32 s4, s13, 0x88000
	s_mul_i32 s12, s12, 0x22000
	v_exp_f32_e32 v86, v93
	s_add_i32 s66, s4, s12
	s_lshl_b64 s[4:5], s[66:67], 1
	v_mul_u32_u24_e32 v4, 0x880, v4
	s_add_u32 s4, s8, s4
	s_mul_i32 s6, s13, 0x880
	v_add_u32_e32 v12, 0, v96
	v_lshl_add_u32 v123, v92, 2, 0
	v_lshlrev_b32_e32 v5, 9, v5
	v_sub_u32_e32 v126, 0, v64
	v_lshlrev_b32_e32 v64, 1, v4
	s_addc_u32 s5, s9, s5
	v_mov_b32_e32 v0, 0
	s_mov_b32 s7, 0
	v_mov_b32_e32 v99, v98
	v_mov_b32_e32 v100, v86
	v_mov_b32_e32 v101, v86
	v_mov_b32_e32 v91, v92
	v_mov_b32_e32 v102, v88
	v_mov_b32_e32 v103, v88
	v_add_u32_e32 v124, 32, v10
	v_or_b32_e32 v125, s6, v3
	v_lshl_add_u64 v[114:115], s[4:5], 0, v[64:65]
	v_add_u32_e32 v127, v9, v6
	v_add_u32_e32 v128, v12, v8
	v_add_u32_e32 v129, v123, v5
	s_lshl_b32 s66, s14, 1
	v_mov_b32_e32 v1, v0
	v_mov_b32_e32 v2, v0
	v_mov_b32_e32 v3, v0
	v_mov_b32_e32 v4, v0
	v_mov_b32_e32 v5, v0
	v_mov_b32_e32 v6, v0
	v_mov_b32_e32 v7, v0
	v_mov_b32_e32 v8, v0
	v_mov_b32_e32 v9, v0
	v_mov_b32_e32 v10, v0
	v_mov_b32_e32 v11, v0
	v_mov_b32_e32 v12, v0
	v_mov_b32_e32 v13, v0
	v_mov_b32_e32 v14, v0
	v_mov_b32_e32 v15, v0
	v_lshlrev_b32_e32 v206, 1, v94
	v_add_u32_e32 v206, s14, v206
	v_lshlrev_b32_e32 v207, 1, v90
	v_sub_u32_e32 v206, v206, v207
	v_add_u32_e32 v206, 0x400, v206
	v_mov_b32_e32 v207, 0
	v_and_b32_e32 v232, 32, v162
	v_lshrrev_b32_e32 v232, 2, v232
	v_mov_b32_e32 v233, 0
	v_lshl_add_u64 v[108:109], v[108:109], 0, v[232:233]
	v_lshl_add_u64 v[110:111], v[110:111], 0, v[232:233]
